# P1 (both layers): x-row loads re-mapped so each load covers 1 KB contiguous (full cache lines) + v_permlane32_swap to restore the lane layout
# speedup vs baseline: 1.0789x; 1.0027x over previous
.LBB0_124:
	s_or_b64 exec, exec, s[0:1]
	s_add_u32 s30, s14, 0x1670000
	s_addc_u32 s31, s15, 0
	s_add_u32 s0, s14, 0x1340000
	s_addc_u32 s1, s15, 0
	s_lshl_b32 s20, s13, 3
	s_abs_i32 s5, s20
	s_waitcnt lgkmcnt(0)
	v_cvt_f32_u32_e32 v0, s5
	v_writelane_b32 v250, s0, 6
	s_bfe_i32 s4, s13, 0x1001c
	s_mov_b32 s52, 0
	v_rcp_iflag_f32_e32 v1, v0
	v_writelane_b32 v250, s1, 7
	s_sub_i32 s0, 0, s5
	v_mov_b32_e32 v0, v154
	v_mul_f32_e32 v1, 0x4f7ffffe, v1
	v_cvt_u32_f32_e32 v1, v1
	s_movk_i32 s53, 0x4000
	s_barrier
	v_readfirstlane_b32 s1, v1
	s_mul_i32 s0, s0, s1
	s_mul_hi_u32 s0, s1, s0
	s_add_i32 s0, s1, s0
	v_writelane_b32 v250, s0, 8
	s_lshr_b32 s0, s0, 18
	s_mul_i32 s1, s0, s5
	s_sub_i32 s1, 0x4000, s1
	s_add_i32 s2, s0, 1
	s_sub_i32 s3, s1, s5
	s_cmp_ge_u32 s1, s5
	s_cselect_b32 s0, s2, s0
	s_cselect_b32 s1, s3, s1
	s_add_i32 s2, s0, 1
	s_cmp_ge_u32 s1, s5
	s_cselect_b32 s0, s2, s0
	s_xor_b32 s0, s0, s4
	v_writelane_b32 v250, s5, 10
	s_sub_i32 s21, s0, s4
	v_writelane_b32 v250, s4, 12
	s_cmp_gt_i32 s21, -1
	v_writelane_b32 v250, s0, 13
	s_cselect_b64 s[0:1], -1, 0
	v_writelane_b32 v250, s0, 14
	s_cmp_lt_i32 s21, 0
	s_nop 0
	v_writelane_b32 v250, s1, 15
	s_cbranch_scc1 .LBB0_154
	s_mul_i32 s1, s21, s20
	v_ashrrev_i32_e32 v1, 6, v0
	s_sub_i32 s0, 0x4280, s1
	v_mul_lo_u32 v2, v1, s13
	v_lshlrev_b32_e32 v0, 3, v0
	s_add_u32 s4, s74, 0x4500000
	v_add_u32_e32 v2, s91, v2
	v_and_b32_e32 v16, 0x1f8, v0
	s_addc_u32 s5, s75, 0
	v_cmp_gt_i32_e32 vcc, s0, v2
	v_add_u32_e32 v17, s1, v2
	v_mov_b32_e32 v19, 0
	v_or_b32_e32 v0, 4, v16
	v_or_b32_e32 v2, 0x200, v16
	v_or_b32_e32 v4, 0x204, v16
	s_add_u32 s6, s74, 0x4200000
	v_lshlrev_b32_e32 v18, 2, v16
	s_addc_u32 s7, s75, 0
	v_lshl_add_u64 v[20:21], s[38:39], 0, v[18:19]
	v_lshl_add_u64 v[22:23], s[24:25], 0, v[18:19]
	v_lshl_add_u32 v42, s91, 3, v1
	v_lshlrev_b32_e32 v42, 3, v42
	s_add_i32 s72, s21, 1
	s_mov_b64 s[8:9], 0
	s_movk_i32 s73, 0x4200
	s_movk_i32 s76, 0x7ff
	v_mov_b32_e32 v43, 0x358637bd
	s_mov_b32 s77, 0x800000
	s_movk_i32 s78, 0x6000
	s_mov_b64 s[22:23], 0x1000
	v_lshlrev_b32_e32 v24, 2, v0
	v_lshlrev_b32_e32 v26, 2, v2
	v_lshlrev_b32_e32 v28, 2, v4
	s_mov_b64 s[36:37], 0x400
	v_lshlrev_b32_e32 v18, 2, v16
	v_mov_b32_e32 v44, 0x3a800000
	v_and_b32_e32 v116, 32, v154
	v_cmp_eq_u32_e64 s[100:101], 0, v116
	v_mov_b32_e32 v120, 0xfffffc10
	v_mov_b32_e32 v121, 16
	v_mov_b32_e32 v122, 0x400
	v_cndmask_b32_e64 v116, v120, 0, s[100:101]
	v_cndmask_b32_e64 v117, -1, 0, s[100:101]
	v_cndmask_b32_e64 v118, v121, v122, s[100:101]
	v_mov_b32_e32 v119, 0
	s_branch .LBB0_127

.Lp1_skip0:
	v_add_u32_e32 v25, 0xffffc000, v30
	v_ashrrev_i32_e32 v31, 31, v30
	v_cmp_gt_i32_e64 s[0:1], s53, v30
	v_mov_b32_e32 v2, s19
	v_mov_b32_e32 v3, s17
	v_cndmask_b32_e64 v1, 0, v31, s[0:1]
	v_cndmask_b32_e64 v0, v25, v30, s[0:1]
	v_cndmask_b32_e64 v3, v2, v3, s[0:1]
	v_mov_b32_e32 v2, s18
	v_mov_b32_e32 v4, s16
	v_cndmask_b32_e64 v2, v2, v4, s[0:1]
	v_lshlrev_b64 v[0:1], 12, v[0:1]
	v_lshl_add_u64 v[0:1], v[2:3], 0, v[0:1]
	v_lshl_add_u64 v[0:1], v[0:1], 0, v[18:19]
	v_lshl_add_u64 v[112:113], v[0:1], 0, v[116:117]
	v_lshl_add_u64 v[114:115], v[0:1], 0, v[118:119]
	global_load_dwordx4 v[12:15], v[112:113], off nt
	global_load_dwordx4 v[8:11], v[114:115], off nt
	global_load_dwordx4 v[4:7], v[112:113], off offset:2048 nt
	global_load_dwordx4 v[0:3], v[114:115], off offset:2048 nt
	v_and_b32_e32 v32, 0x7ff, v30
	v_and_b32_e32 v33, 3, v30
	v_cmp_eq_u32_e64 s[2:3], s76, v32
	v_lshrrev_b32_e32 v25, 2, v25
	v_ashrrev_i32_e32 v27, 11, v30
	v_cndmask_b32_e64 v32, 0, 1, s[2:3]
	v_cmp_eq_u32_e64 s[2:3], 3, v33
	v_add_u32_e32 v25, 8, v25
	v_cndmask_b32_e64 v34, v25, v27, s[0:1]
	v_cndmask_b32_e64 v33, 0, 1, s[2:3]
	v_cndmask_b32_e64 v32, v33, v32, s[0:1]
	v_and_b32_e32 v25, 1, v32
	v_cmp_eq_u32_e64 s[2:3], 1, v25
	v_mov_b32_e32 v29, v19
	v_mov_b32_e32 v35, v19
	s_waitcnt vmcnt(0)
	v_permlane32_swap_b32_e32 v12, v8
	v_permlane32_swap_b32_e32 v13, v9
	v_permlane32_swap_b32_e32 v14, v10
	v_permlane32_swap_b32_e32 v15, v11
	v_permlane32_swap_b32_e32 v4, v0
	v_permlane32_swap_b32_e32 v5, v1
	v_permlane32_swap_b32_e32 v6, v2
	v_permlane32_swap_b32_e32 v7, v3
	v_mov_b32_e32 v36, v13
	v_mov_b32_e32 v37, v9
	v_mov_b32_e32 v32, v12
	v_mov_b32_e32 v33, v8
	v_mov_b32_e32 v48, v5
	v_mov_b32_e32 v49, v1
	v_pk_mul_f32 v[36:37], v[36:37], v[36:37]
	v_mov_b32_e32 v38, v14
	v_mov_b32_e32 v39, v10
	v_mov_b32_e32 v46, v4
	v_mov_b32_e32 v47, v0
	v_pk_mul_f32 v[48:49], v[48:49], v[48:49]
	v_pk_fma_f32 v[32:33], v[32:33], v[32:33], v[36:37]
	v_mov_b32_e32 v40, v15
	v_mov_b32_e32 v41, v11
	v_mov_b32_e32 v50, v6
	v_mov_b32_e32 v51, v2
	v_pk_fma_f32 v[36:37], v[46:47], v[46:47], v[48:49]
	v_pk_fma_f32 v[32:33], v[38:39], v[38:39], v[32:33]
	v_mov_b32_e32 v52, v7
	v_mov_b32_e32 v53, v3
	v_pk_fma_f32 v[36:37], v[50:51], v[50:51], v[36:37]
	v_pk_fma_f32 v[32:33], v[40:41], v[40:41], v[32:33]
	v_pk_fma_f32 v[36:37], v[52:53], v[52:53], v[36:37]
	v_add_f32_e32 v25, v32, v33
	v_add_f32_e32 v25, v25, v36
	v_add_f32_e32 v25, v25, v37
	v_mov_b64_e32 v[32:33], 0
	s_nop 0
	v_add_f32_dpp v25, v25, v25 row_ror:8 row_mask:0xf bank_mask:0xf bound_ctrl:1
	s_nop 1
	v_add_f32_dpp v25, v25, v25 row_ror:4 row_mask:0xf bank_mask:0xf bound_ctrl:1
	s_nop 1
	v_add_f32_dpp v25, v25, v25 row_ror:2 row_mask:0xf bank_mask:0xf bound_ctrl:1
	s_nop 1
	v_add_f32_dpp v25, v25, v25 row_ror:1 row_mask:0xf bank_mask:0xf bound_ctrl:1
	s_nop 1
	v_mov_b32_dpp v29, v25 row_bcast:15 row_mask:0xa bank_mask:0xf
	v_add_f32_e32 v25, v25, v29
	s_nop 1
	v_mov_b32_dpp v35, v25 row_bcast:31 row_mask:0xc bank_mask:0xf
	v_add_f32_e32 v25, v25, v35
	s_nop 0
	v_readlane_b32 s12, v25, 63
	s_and_saveexec_b64 s[10:11], s[2:3]
	s_cbranch_execz .LBB0_137
	v_cmp_lt_i32_e64 s[0:1], 7, v34
	s_and_saveexec_b64 s[34:35], s[0:1]
	s_xor_b64 s[0:1], exec, s[34:35]
	v_add_u32_e32 v32, -8, v34
	v_mov_b32_e32 v33, v19
	v_lshlrev_b64 v[32:33], 12, v[32:33]
	v_lshl_add_u64 v[32:33], s[4:5], 0, v[32:33]
	s_andn2_saveexec_b64 s[0:1], s[0:1]
	v_ashrrev_i32_e32 v35, 31, v34
	v_lshlrev_b64 v[32:33], 12, v[34:35]
	v_lshl_add_u64 v[32:33], s[6:7], 0, v[32:33]
	s_or_b64 exec, exec, s[0:1]

.LBB0_740:
	s_or_b64 exec, exec, s[0:1]
	v_readlane_b32 s0, v250, 14
	v_readlane_b32 s1, v250, 15
	s_waitcnt lgkmcnt(0)
	v_mov_b32_e32 v0, v154
	s_andn2_b64 vcc, exec, s[0:1]
	s_barrier
	s_cbranch_vccnz .LBB0_770
	s_mul_i32 s1, s21, s20
	s_sub_i32 s0, 0x4280, s1
	s_add_u32 s6, s14, 0x1343000
	s_addc_u32 s7, s15, 0
	s_add_u32 s8, s74, 0x4580000
	v_ashrrev_i32_e32 v1, 6, v0
	s_addc_u32 s9, s75, 0
	v_mul_lo_u32 v2, v1, s13
	v_lshlrev_b32_e32 v0, 3, v0
	s_add_u32 s52, s74, 0x4208000
	v_add_u32_e32 v2, s91, v2
	v_and_b32_e32 v24, 0x1f8, v0
	s_addc_u32 s53, s75, 0
	v_cmp_gt_i32_e32 vcc, s0, v2
	v_mov_b32_e32 v27, 0
	v_or_b32_e32 v0, 4, v24
	s_add_u32 s0, s38, 0x1000
	v_add_u32_e32 v25, s1, v2
	v_or_b32_e32 v2, 0x200, v24
	s_addc_u32 s1, s39, 0
	v_lshlrev_b32_e32 v6, 2, v0
	v_mov_b32_e32 v7, v27
	v_or_b32_e32 v4, 0x204, v24
	v_lshl_add_u64 v[32:33], s[0:1], 0, v[6:7]
	v_lshlrev_b32_e32 v6, 2, v2
	v_lshl_add_u64 v[34:35], s[0:1], 0, v[6:7]
	v_lshlrev_b32_e32 v6, 2, v4
	v_lshlrev_b32_e32 v26, 2, v24
	v_lshl_add_u64 v[36:37], s[0:1], 0, v[6:7]
	v_lshlrev_b32_e32 v6, 1, v24
	v_lshl_add_u64 v[30:31], s[0:1], 0, v[26:27]
	v_lshl_add_u64 v[38:39], s[74:75], 0, v[6:7]
	v_lshl_add_u64 v[6:7], s[24:25], 0, v[26:27]
	s_mov_b64 s[0:1], 0x80000
	v_lshl_add_u64 v[40:41], v[6:7], 0, s[0:1]
	v_readlane_b32 s0, v250, 23
	v_lshl_add_u64 v[28:29], s[40:41], 0, v[26:27]
	s_add_i32 s34, s21, 1
	v_add_u32_e32 v69, s0, v1
	s_mov_b32 s35, 0
	s_mov_b64 s[24:25], 0
	v_mov_b32_e32 v70, 0x358637bd
	s_mov_b32 s48, 0x800000
	s_movk_i32 s49, 0x6000
	v_lshlrev_b32_e32 v42, 2, v0
	v_lshlrev_b32_e32 v44, 2, v4
	s_mov_b64 s[38:39], 0x400
	v_lshlrev_b32_e32 v26, 2, v24
	v_mov_b32_e32 v71, 0x3a800000
	v_lshlrev_b32_e32 v46, 2, v2
	v_and_b32_e32 v116, 32, v154
	v_cmp_eq_u32_e64 s[100:101], 0, v116
	v_mov_b32_e32 v120, 0xfffffc10
	v_mov_b32_e32 v121, 16
	v_mov_b32_e32 v122, 0x400
	v_cndmask_b32_e64 v116, v120, 0, s[100:101]
	v_cndmask_b32_e64 v117, -1, 0, s[100:101]
	v_cndmask_b32_e64 v118, v121, v122, s[100:101]
	v_mov_b32_e32 v119, 0
	s_branch .LBB0_743

.LBB0_745:
	v_mov_b32_e32 v0, 2
	s_and_saveexec_b64 s[72:73], s[0:1]
	s_cbranch_execz .LBB0_765
	s_movk_i32 s0, 0x4200
	v_cmp_gt_i32_e64 s[0:1], s0, v48
	s_and_saveexec_b64 s[2:3], s[0:1]
	s_xor_b64 s[80:81], exec, s[2:3]
	s_cbranch_execz .LBB0_762
	s_movk_i32 s0, 0x4000
	v_add_u32_e32 v0, 0xffffc000, v48
	v_cmp_gt_i32_e64 s[2:3], s0, v48
	v_lshrrev_b32_e32 v1, 2, v0
	v_ashrrev_i32_e32 v49, 31, v48
	v_mov_b32_e32 v2, s19
	v_mov_b32_e32 v3, s17
	v_add_u32_e32 v16, 8, v1
	v_cndmask_b32_e64 v1, 0, v49, s[2:3]
	v_cndmask_b32_e64 v0, v0, v48, s[2:3]
	v_cndmask_b32_e64 v3, v2, v3, s[2:3]
	v_mov_b32_e32 v2, s18
	v_mov_b32_e32 v4, s16
	v_cndmask_b32_e64 v2, v2, v4, s[2:3]
	v_lshlrev_b64 v[0:1], 12, v[0:1]
	v_ashrrev_i32_e32 v17, 11, v48
	v_lshl_add_u64 v[0:1], v[2:3], 0, v[0:1]
	v_cndmask_b32_e64 v50, v16, v17, s[2:3]
	v_lshlrev_b64 v[16:17], 12, v[48:49]
	v_lshl_add_u64 v[4:5], v[0:1], 0, v[26:27]
	v_lshl_add_u64 v[56:57], v[38:39], 0, v[16:17]
	v_lshl_add_u64 v[112:113], v[4:5], 0, v[116:117]
	v_lshl_add_u64 v[114:115], v[4:5], 0, v[118:119]
	global_load_dwordx4 v[12:15], v[112:113], off nt
	global_load_dwordx4 v[8:11], v[114:115], off nt
	global_load_dwordx4 v[4:7], v[112:113], off offset:2048 nt
	global_load_dwordx4 v[0:3], v[114:115], off offset:2048 nt
	v_mov_b32_e32 v45, v27
	global_load_dwordx4 v[52:55], v[56:57], off nt
	v_mov_b32_e32 v47, v27
	s_waitcnt vmcnt(0)
	v_permlane32_swap_b32_e32 v12, v8
	v_permlane32_swap_b32_e32 v13, v9
	v_permlane32_swap_b32_e32 v14, v10
	v_permlane32_swap_b32_e32 v15, v11
	v_permlane32_swap_b32_e32 v4, v0
	v_permlane32_swap_b32_e32 v5, v1
	v_permlane32_swap_b32_e32 v6, v2
	v_permlane32_swap_b32_e32 v7, v3
	v_cvt_f32_f16_sdwa v19, v52 dst_sel:DWORD dst_unused:UNUSED_PAD src0_sel:WORD_1
	v_cvt_f32_f16_sdwa v17, v54 dst_sel:DWORD dst_unused:UNUSED_PAD src0_sel:WORD_1
	v_cvt_f32_f16_e32 v18, v52
	v_cvt_f32_f16_e32 v16, v54
	v_cvt_f32_f16_e32 v22, v53
	v_cvt_f32_f16_e32 v20, v55
	v_cvt_f32_f16_sdwa v23, v53 dst_sel:DWORD dst_unused:UNUSED_PAD src0_sel:WORD_1
	v_cvt_f32_f16_sdwa v21, v55 dst_sel:DWORD dst_unused:UNUSED_PAD src0_sel:WORD_1
	v_mov_b32_e32 v54, v19
	v_mov_b32_e32 v55, v17
	v_mov_b32_e32 v52, v18
	v_mov_b32_e32 v53, v16
	v_pk_mul_f32 v[54:55], v[54:55], v[54:55]
	s_nop 0
	v_pk_fma_f32 v[52:53], v[52:53], v[52:53], v[54:55]
	v_mov_b32_e32 v54, v22
	v_mov_b32_e32 v55, v20
	v_pk_fma_f32 v[52:53], v[54:55], v[54:55], v[52:53]
	v_mov_b32_e32 v54, v23
	v_mov_b32_e32 v55, v21
	v_pk_fma_f32 v[60:61], v[54:55], v[54:55], v[52:53]
	global_load_dwordx4 v[52:55], v[56:57], off offset:1024 nt
	v_add_f32_e32 v43, v60, v61
	s_waitcnt vmcnt(0)
	v_cvt_f32_f16_sdwa v57, v52 dst_sel:DWORD dst_unused:UNUSED_PAD src0_sel:WORD_1
	v_cvt_f32_f16_e32 v58, v53
	v_cvt_f32_f16_sdwa v59, v53 dst_sel:DWORD dst_unused:UNUSED_PAD src0_sel:WORD_1
	v_cvt_f32_f16_sdwa v53, v54 dst_sel:DWORD dst_unused:UNUSED_PAD src0_sel:WORD_1
	v_cvt_f32_f16_e32 v56, v52
	v_cvt_f32_f16_e32 v52, v54
	v_cvt_f32_f16_e32 v54, v55
	v_cvt_f32_f16_sdwa v55, v55 dst_sel:DWORD dst_unused:UNUSED_PAD src0_sel:WORD_1
	v_mov_b32_e32 v64, v57
	v_mov_b32_e32 v65, v53
	v_mov_b32_e32 v62, v56
	v_mov_b32_e32 v63, v52
	v_pk_mul_f32 v[64:65], v[64:65], v[64:65]
	s_nop 0
	v_pk_fma_f32 v[62:63], v[62:63], v[62:63], v[64:65]
	v_mov_b32_e32 v64, v58
	v_mov_b32_e32 v65, v54
	v_pk_fma_f32 v[62:63], v[64:65], v[64:65], v[62:63]
	v_mov_b32_e32 v64, v59
	v_mov_b32_e32 v65, v55
	v_pk_fma_f32 v[62:63], v[64:65], v[64:65], v[62:63]
	s_nop 0
	v_add_f32_e32 v43, v43, v62
	v_add_f32_e32 v43, v43, v63
	s_nop 1
	v_add_f32_dpp v43, v43, v43 row_ror:8 row_mask:0xf bank_mask:0xf bound_ctrl:1
	s_nop 1
	v_add_f32_dpp v43, v43, v43 row_ror:4 row_mask:0xf bank_mask:0xf bound_ctrl:1
	s_nop 1
	v_add_f32_dpp v43, v43, v43 row_ror:2 row_mask:0xf bank_mask:0xf bound_ctrl:1
	s_nop 1
	v_add_f32_dpp v43, v43, v43 row_ror:1 row_mask:0xf bank_mask:0xf bound_ctrl:1
	s_nop 1
	v_mov_b32_dpp v45, v43 row_bcast:15 row_mask:0xa bank_mask:0xf
	v_add_f32_e32 v43, v43, v45
	v_mov_b32_e32 v45, v27
	s_nop 1
	v_mov_b32_dpp v45, v43 row_bcast:31 row_mask:0xc bank_mask:0xf
	v_add_f32_e32 v43, v43, v45
	s_nop 0
	v_readlane_b32 s0, v43, 63
	s_nop 1
	v_fma_f32 v43, s0, v71, v70
	v_cmp_gt_f32_e64 s[0:1], s48, v43
	v_mul_f32_e32 v45, 0x4b800000, v43
	s_nop 0
	v_cndmask_b32_e64 v43, v43, v45, s[0:1]
	v_rsq_f32_e32 v43, v43
	s_nop 0
	v_mul_f32_e32 v45, 0x45800000, v43
	v_cndmask_b32_e64 v68, v43, v45, s[0:1]
	v_readlane_b32 s0, v250, 6
	v_readlane_b32 s1, v250, 7
	v_pk_mul_f32 v[22:23], v[22:23], v[68:69] op_sel_hi:[1,0]
	v_pk_mul_f32 v[18:19], v[18:19], v[68:69] op_sel_hi:[1,0]
	v_mov_b64_e32 v[60:61], s[0:1]
	v_mad_i64_i32 v[60:61], s[0:1], v50, s49, v[60:61]
	s_mov_b64 s[0:1], 0x2000
	s_nop 0
	v_lshl_add_u64 v[80:81], v[60:61], 0, s[0:1]
	global_load_dwordx4 v[60:63], v[28:29], off offset:16
	global_load_dwordx4 v[64:67], v[28:29], off
	v_lshl_add_u64 v[76:77], v[80:81], 0, v[26:27]
	global_load_dwordx4 v[72:75], v[76:77], off offset:16
	s_nop 0
	global_load_dwordx4 v[76:79], v[76:77], off
	v_pk_mul_f32 v[56:57], v[56:57], v[68:69] op_sel_hi:[1,0]
	v_pk_mul_f32 v[58:59], v[58:59], v[68:69] op_sel_hi:[1,0]
	s_movk_i32 s0, 0x7ff
	s_waitcnt vmcnt(2)
	v_pk_mul_f32 v[18:19], v[64:65], v[18:19]
	v_pk_mul_f32 v[22:23], v[66:67], v[22:23]
	s_waitcnt vmcnt(0)
	v_pk_fma_f32 v[66:67], v[76:77], v[18:19], v[12:13]
	v_pk_fma_f32 v[64:65], v[78:79], v[22:23], v[14:15]
	v_pk_mul_f32 v[12:13], v[20:21], v[68:69] op_sel_hi:[1,0]
	v_pk_mul_f32 v[14:15], v[16:17], v[68:69] op_sel_hi:[1,0]
	v_pk_mul_f32 v[12:13], v[62:63], v[12:13]
	v_pk_mul_f32 v[14:15], v[60:61], v[14:15]
	v_pk_fma_f32 v[60:61], v[74:75], v[12:13], v[10:11]
	v_pk_fma_f32 v[62:63], v[72:73], v[14:15], v[8:9]
	global_load_dwordx4 v[8:11], v[28:29], off offset:2064
	global_load_dwordx4 v[12:15], v[28:29], off offset:2048
	v_lshl_add_u64 v[20:21], v[80:81], 0, v[46:47]
	global_load_dwordx4 v[16:19], v[20:21], off offset:16
	s_nop 0
	global_load_dwordx4 v[20:23], v[20:21], off
	s_waitcnt vmcnt(2)
	v_pk_mul_f32 v[12:13], v[12:13], v[56:57]
	v_pk_mul_f32 v[14:15], v[14:15], v[58:59]
	s_waitcnt vmcnt(0)
	v_pk_fma_f32 v[20:21], v[20:21], v[12:13], v[4:5]
	v_pk_mul_f32 v[4:5], v[54:55], v[68:69] op_sel_hi:[1,0]
	v_pk_fma_f32 v[22:23], v[22:23], v[14:15], v[6:7]
	v_pk_mul_f32 v[6:7], v[52:53], v[68:69] op_sel_hi:[1,0]
	v_pk_mul_f32 v[4:5], v[10:11], v[4:5]
	v_pk_mul_f32 v[6:7], v[8:9], v[6:7]
	v_pk_fma_f32 v[12:13], v[18:19], v[4:5], v[2:3]
	v_mov_b32_e32 v2, v67
	v_mov_b32_e32 v3, v63
	v_pk_fma_f32 v[14:15], v[16:17], v[6:7], v[0:1]
	v_mov_b32_e32 v0, v66
	v_mov_b32_e32 v1, v62
	v_pk_mul_f32 v[2:3], v[2:3], v[2:3]
	v_mov_b32_e32 v4, v15
	v_pk_fma_f32 v[0:1], v[0:1], v[0:1], v[2:3]
	v_mov_b32_e32 v2, v64
	v_mov_b32_e32 v3, v60
	v_pk_fma_f32 v[0:1], v[2:3], v[2:3], v[0:1]
	v_mov_b32_e32 v2, v65
	v_mov_b32_e32 v3, v61
	v_mov_b32_e32 v5, v21
	v_pk_fma_f32 v[0:1], v[2:3], v[2:3], v[0:1]
	v_mov_b32_e32 v2, v14
	v_mov_b32_e32 v3, v20
	v_pk_mul_f32 v[4:5], v[4:5], v[4:5]
	v_add_f32_e32 v0, v0, v1
	v_pk_fma_f32 v[2:3], v[2:3], v[2:3], v[4:5]
	v_mov_b32_e32 v4, v12
	v_mov_b32_e32 v5, v22
	v_pk_fma_f32 v[2:3], v[4:5], v[4:5], v[2:3]
	v_mov_b32_e32 v4, v13
	v_mov_b32_e32 v5, v23
	v_pk_fma_f32 v[2:3], v[4:5], v[4:5], v[2:3]
	v_mov_b32_e32 v1, v27
	v_add_f32_e32 v0, v3, v0
	v_add_f32_e32 v0, v2, v0
	v_mov_b64_e32 v[16:17], 0
	s_nop 0
	v_add_f32_dpp v0, v0, v0 row_ror:8 row_mask:0xf bank_mask:0xf bound_ctrl:1
	s_nop 1
	v_add_f32_dpp v0, v0, v0 row_ror:4 row_mask:0xf bank_mask:0xf bound_ctrl:1
	s_nop 1
	v_add_f32_dpp v0, v0, v0 row_ror:2 row_mask:0xf bank_mask:0xf bound_ctrl:1
	s_nop 1
	v_add_f32_dpp v0, v0, v0 row_ror:1 row_mask:0xf bank_mask:0xf bound_ctrl:1
	s_nop 1
	v_mov_b32_dpp v1, v0 row_bcast:15 row_mask:0xa bank_mask:0xf
	v_add_f32_e32 v0, v0, v1
	v_mov_b32_e32 v1, v27
	s_nop 1
	v_mov_b32_dpp v1, v0 row_bcast:31 row_mask:0xc bank_mask:0xf
	v_add_f32_e32 v0, v0, v1
	s_nop 0
	v_readlane_b32 s10, v0, 63
	v_and_b32_e32 v0, 0x7ff, v48
	v_cmp_eq_u32_e64 s[0:1], s0, v0
	v_and_b32_e32 v0, 3, v48
	v_cmp_eq_u32_e64 s[4:5], 3, v0
	v_cndmask_b32_e64 v0, 0, 1, s[0:1]
	s_nop 0
	v_cndmask_b32_e64 v1, 0, 1, s[4:5]
	v_cndmask_b32_e64 v0, v1, v0, s[2:3]
	v_and_b32_e32 v0, 1, v0
	v_cmp_eq_u32_e64 s[2:3], 1, v0
	s_and_saveexec_b64 s[4:5], s[2:3]
	s_cbranch_execz .LBB0_753
	v_ashrrev_i32_e32 v51, 31, v50
	v_cmp_lt_i32_e64 s[0:1], 7, v50
	s_and_saveexec_b64 s[42:43], s[0:1]
	s_xor_b64 s[0:1], exec, s[42:43]
	v_add_u32_e32 v0, -8, v50
	v_mov_b32_e32 v1, v27
	v_lshlrev_b64 v[0:1], 12, v[0:1]
	v_lshl_add_u64 v[16:17], s[8:9], 0, v[0:1]
	s_andn2_saveexec_b64 s[0:1], s[0:1]
	v_lshlrev_b64 v[0:1], 12, v[50:51]
	v_lshl_add_u64 v[16:17], s[52:53], 0, v[0:1]
	s_or_b64 exec, exec, s[0:1]
